# XCD-local barriers for seams 1,8,9,10 (skip L2 wb + top-level sync when census ok)
# speedup vs baseline: 1.0233x; 1.0233x over previous
.LBB0_123:
	s_and_saveexec_b64 s[34:35], s[92:93]
	s_cbranch_execz .LBB0_127
	v_mov_b32_e32 v0, 0x21280000
	global_load_dword v1, v0, s[56:57] offset:1024 sc1
	global_load_dword v2, v0, s[56:57] offset:1280 sc1
	global_load_dword v3, v0, s[56:57] offset:1536 sc1
	global_load_dword v4, v0, s[56:57] offset:1792 sc1
	global_load_dword v5, v0, s[56:57] offset:2048 sc1
	global_load_dword v6, v0, s[56:57] offset:2304 sc1
	global_load_dword v7, v0, s[56:57] offset:2560 sc1
	global_load_dword v8, v0, s[56:57] offset:2816 sc1
	global_load_dword v9, v0, s[56:57] offset:3072 sc1
	global_load_dword v10, v0, s[56:57] offset:3328 sc1
	global_load_dword v11, v0, s[56:57] offset:3584 sc1
	global_load_dword v12, v0, s[56:57] offset:3840 sc1
	v_mov_b32_e32 v0, 0x21281000
	global_load_dword v13, v0, s[56:57] sc1
	global_load_dword v14, v0, s[56:57] offset:256 sc1
	global_load_dword v15, v0, s[56:57] offset:512 sc1
	global_load_dword v16, v0, s[56:57] offset:768 sc1
	s_and_b32 s0, s90, 7
	s_cmp_eq_u32 s0, 0
	s_cselect_b64 s[36:37], -1, 0
	s_lshr_b32 s12, s90, 3
	v_mov_b32_e32 v0, s88
	s_waitcnt vmcnt(15)
	v_cmp_eq_u32_e32 vcc, s12, v1
	s_waitcnt vmcnt(14)
	v_cmp_eq_u32_e64 s[0:1], s12, v2
	s_and_b64 s[36:37], s[36:37], vcc
	s_waitcnt vmcnt(13)
	v_cmp_eq_u32_e64 s[2:3], s12, v3
	s_and_b64 s[0:1], s[36:37], s[0:1]
	s_waitcnt vmcnt(12)
	v_cmp_eq_u32_e64 s[4:5], s12, v4
	s_and_b64 s[0:1], s[0:1], s[2:3]
	s_waitcnt vmcnt(11)
	v_cmp_eq_u32_e64 s[6:7], s12, v5
	s_and_b64 s[0:1], s[0:1], s[4:5]
	s_waitcnt vmcnt(10)
	v_cmp_eq_u32_e64 s[8:9], s12, v6
	s_and_b64 s[0:1], s[0:1], s[6:7]
	s_waitcnt vmcnt(9)
	v_cmp_eq_u32_e64 s[10:11], s12, v7
	s_and_b64 s[0:1], s[0:1], s[8:9]
	s_waitcnt vmcnt(8)
	v_cmp_eq_u32_e64 s[12:13], s12, v8
	s_and_b64 s[0:1], s[0:1], s[10:11]
	s_waitcnt vmcnt(7)
	v_cmp_eq_u32_e64 s[14:15], 0, v9
	s_and_b64 s[0:1], s[0:1], s[12:13]
	s_waitcnt vmcnt(6)
	v_cmp_eq_u32_e64 s[16:17], 0, v10
	s_and_b64 s[0:1], s[0:1], s[14:15]
	s_waitcnt vmcnt(5)
	v_cmp_eq_u32_e64 s[18:19], 0, v11
	s_and_b64 s[0:1], s[0:1], s[16:17]
	s_waitcnt vmcnt(4)
	v_cmp_eq_u32_e64 s[20:21], 0, v12
	s_and_b64 s[0:1], s[0:1], s[18:19]
	s_waitcnt vmcnt(3)
	v_cmp_eq_u32_e64 s[22:23], 0, v13
	s_and_b64 s[0:1], s[0:1], s[20:21]
	s_waitcnt vmcnt(2)
	v_cmp_eq_u32_e64 s[24:25], 0, v14
	s_and_b64 s[0:1], s[0:1], s[22:23]
	s_waitcnt vmcnt(1)
	v_cmp_eq_u32_e64 s[26:27], 0, v15
	s_and_b64 s[0:1], s[0:1], s[24:25]
	s_waitcnt vmcnt(0)
	v_cmp_eq_u32_e64 s[28:29], 0, v16
	s_and_b64 s[0:1], s[0:1], s[26:27]
	s_and_b64 s[0:1], s[0:1], s[28:29]
	s_andn2_b64 vcc, exec, s[0:1]
	v_mov_b32_e32 v17, 0
	s_cbranch_vccnz .LBB0_126
	v_mov_b32_e32 v17, 1
	s_add_i32 s0, 0, 0x23fc8
	v_mov_b32_e32 v0, s0
	ds_read_b32 v0, v0
	s_waitcnt lgkmcnt(0)
	v_lshlrev_b32_e32 v0, 3, v0
	v_add_u32_e32 v0, s96, v0
.LBB0_126:
	s_add_i32 s0, 0, 0x23fcc
	v_mov_b32_e32 v1, s0
	ds_write_b32 v1, v0
	ds_write_b32 v1, v17 offset:4

.LBB0_182:
	s_andn2_saveexec_b64 s[6:7], s[6:7]
	s_cbranch_execz .LBB0_202
	s_mov_b64 s[6:7], exec
	v_mov_b32_e32 v1, 0x23fd0
	ds_read_b32 v2, v1
	s_waitcnt lgkmcnt(0)
	v_cmp_ne_u32_e32 vcc, 0, v2
	s_cbranch_vccnz .LBB0_199
	buffer_wbl2 sc1
	s_waitcnt lgkmcnt(0)
	s_waitcnt vmcnt(0)
	v_mbcnt_lo_u32_b32 v1, s6, 0
	v_mbcnt_hi_u32_b32 v1, s7, v1
	v_cmp_eq_u32_e32 vcc, 0, v1
	s_and_saveexec_b64 s[8:9], vcc
	s_cbranch_execz .LBB0_185
	s_bcnt1_i32_b64 s6, s[6:7]
	v_mov_b32_e32 v2, 0x21283000
	v_mov_b32_e32 v3, s6
	global_atomic_add v2, v2, v3, s[56:57] offset:1024 sc0
